# MLA loop: the 5 LDS-DMA pieces per tile spread over the S0 MFMA chain instead of issued together after the barrier
# speedup vs baseline: 1.0049x; 1.0049x over previous
.Lmla_loop:
	ds_read_b128 v[230:233], v193 offset:57344
	ds_read_b128 v[234:237], v186 offset:57344
	ds_read_b128 v[238:241], v187 offset:57344
	ds_read_b128 v[242:245], v188 offset:57344
	s_cmp_lt_u32 s58, s18
	s_cselect_b32 s0, 0, s18
	s_cselect_b32 s1, s6, s13
	s_lshl_b32 s0, s0, 6
	s_sub_i32 s0, s1, s0
	s_add_i32 s0, s51, s0
	s_ashr_i32 s1, s0, 31
	s_lshl_b64 s[10:11], s[0:1], 12
	s_add_u32 s16, s20, s10
	s_addc_u32 s17, s21, s11
	v_exp_f32_e32 v64, v64
	v_exp_f32_e32 v65, v65
	v_add_f32_e32 v212, v64, v212
	v_exp_f32_e32 v66, v66
	v_add_f32_e32 v212, v65, v212
	v_exp_f32_e32 v67, v67
	s_waitcnt lgkmcnt(3)
	v_mfma_f32_32x32x16_bf16 v[80:95], v[230:233], v[124:127], 0
	ds_read_b128 v[230:233], v189 offset:57344
	s_cmp_eq_u32 s58, 2
	s_cbranch_scc1 .Lmla_skipv0_o
	s_mov_b32 m0, s54
	v_lshl_add_u64 v[254:255], v[164:165], 1, s[100:101]
	global_load_lds_dwordx4 v[254:255], off
.Lmla_skipv0_o:
	v_add_f32_e32 v212, v66, v212
	v_exp_f32_e32 v68, v68
	v_add_f32_e32 v212, v67, v212
	v_exp_f32_e32 v69, v69
	s_waitcnt lgkmcnt(3)
	v_mfma_f32_32x32x16_bf16 v[80:95], v[234:237], v[120:123], v[80:95]
	ds_read_b128 v[234:237], v190 offset:57344
	s_cmp_eq_u32 s58, 2
	s_cbranch_scc1 .Lmla_skipv1_o
	s_mov_b32 m0, s55
	v_lshl_add_u64 v[254:255], v[166:167], 1, s[100:101]
	global_load_lds_dwordx4 v[254:255], off
.Lmla_skipv1_o:
	v_add_f32_e32 v212, v68, v212
	v_exp_f32_e32 v70, v70
	v_add_f32_e32 v212, v69, v212
	v_exp_f32_e32 v71, v71
	s_waitcnt lgkmcnt(3)
	v_mfma_f32_32x32x16_bf16 v[80:95], v[238:241], v[116:119], v[80:95]
	ds_read_b128 v[238:241], v191 offset:57344
	v_add_f32_e32 v212, v70, v212
	v_exp_f32_e32 v72, v72
	v_add_f32_e32 v212, v71, v212
	v_exp_f32_e32 v73, v73
	s_waitcnt lgkmcnt(3)
	v_mfma_f32_32x32x16_bf16 v[80:95], v[242:245], v[112:115], v[80:95]
	ds_read_b128 v[242:245], v192 offset:57344
	s_mov_b32 m0, s23
	v_lshl_add_u64 v[254:255], v[160:161], 1, s[16:17]
	global_load_lds_dwordx4 v[254:255], off
	v_add_f32_e32 v212, v72, v212
	v_exp_f32_e32 v74, v74
	v_add_f32_e32 v212, v73, v212
	v_exp_f32_e32 v75, v75
	s_waitcnt lgkmcnt(3)
	v_mfma_f32_32x32x16_bf16 v[80:95], v[230:233], v[108:111], v[80:95]
	v_add_u32_e32 v211, 0x6000, v203
	ds_read_b128 v[230:233], v211 offset:49152
	v_add_f32_e32 v212, v74, v212
	v_exp_f32_e32 v76, v76
	v_add_f32_e32 v212, v75, v212
	v_exp_f32_e32 v77, v77
	s_waitcnt lgkmcnt(3)
	v_mfma_f32_32x32x16_bf16 v[80:95], v[234:237], v[104:107], v[80:95]
	v_add_u32_e32 v211, 0x6000, v204
	ds_read_b128 v[234:237], v211 offset:49152
	s_mov_b32 m0, s7
	v_lshl_add_u64 v[254:255], v[162:163], 1, s[16:17]
	global_load_lds_dwordx4 v[254:255], off
	v_add_f32_e32 v212, v76, v212
	v_exp_f32_e32 v78, v78
	v_add_f32_e32 v212, v77, v212
	v_exp_f32_e32 v79, v79
	s_waitcnt lgkmcnt(3)
	v_mfma_f32_32x32x16_bf16 v[80:95], v[238:241], v[100:103], v[80:95]
	v_add_u32_e32 v211, 0x6000, v205
	ds_read_b128 v[238:241], v211 offset:49152
	v_add_f32_e32 v212, v78, v212
	v_add_f32_e32 v212, v79, v212
	v_mov_b32_e32 v213, v212
	s_waitcnt lgkmcnt(3)
	v_mfma_f32_32x32x16_bf16 v[80:95], v[242:245], v[96:99], v[80:95]
	v_add_u32_e32 v211, 0x6000, v206
	ds_read_b128 v[242:245], v211 offset:49152
	s_mov_b32 m0, s30
	v_mad_i64_i32 v[254:255], s[0:1], s0, v180, v[168:169]
	global_load_lds_dwordx4 v[254:255], off
	s_add_u32 s100, s16, 0x100
	s_addc_u32 s101, s17, 0
	v_cvt_pk_bf16_f32 v152, v64, v65
	v_cvt_pk_bf16_f32 v153, v66, v67
	v_cvt_pk_bf16_f32 v154, v68, v69
	s_waitcnt lgkmcnt(3)
	v_mfma_f32_32x32x16_bf16 v[80:95], v[230:233], v[128:131], v[80:95]
	v_add_u32_e32 v211, v209, v194
	ds_read_b128 v[230:233], v211 offset:8192
	v_cvt_pk_bf16_f32 v155, v70, v71
	v_cvt_pk_bf16_f32 v156, v72, v73
	v_cvt_pk_bf16_f32 v157, v74, v75
	s_waitcnt lgkmcnt(3)
	v_mfma_f32_32x32x16_bf16 v[80:95], v[234:237], v[132:135], v[80:95]
	v_add_u32_e32 v211, v209, v195
	ds_read_b128 v[234:237], v211 offset:8192
	v_cvt_pk_bf16_f32 v158, v76, v77
	v_cvt_pk_bf16_f32 v159, v78, v79
	v_permlane32_swap_b32_e32 v212, v213
	s_waitcnt lgkmcnt(3)
	v_mfma_f32_32x32x16_bf16 v[80:95], v[238:241], v[136:139], v[80:95]
	v_add_u32_e32 v211, v209, v196
	ds_read_b128 v[238:241], v211 offset:8192
	v_add_f32_e32 v252, v212, v213
	v_fma_f32 v183, v207, v183, v252
	v_permlane32_swap_b32_e32 v152, v154
	s_waitcnt lgkmcnt(3)
	v_mfma_f32_32x32x16_bf16 v[80:95], v[242:245], v[140:143], v[80:95]
	v_add_u32_e32 v211, v209, v197
	ds_read_b128 v[242:245], v211 offset:8192
	v_permlane32_swap_b32_e32 v153, v155
	v_permlane32_swap_b32_e32 v156, v158
	v_permlane32_swap_b32_e32 v157, v159
	s_waitcnt lgkmcnt(3)
	v_mfma_f32_32x32x16_bf16 v[64:79], v[230:233], v[124:127], 0
	v_add_u32_e32 v211, v209, v198
	ds_read_b128 v[230:233], v211 offset:8192
	s_waitcnt lgkmcnt(3)
	v_mfma_f32_32x32x16_bf16 v[64:79], v[234:237], v[120:123], v[64:79]
	v_add_u32_e32 v211, v209, v199
	ds_read_b128 v[234:237], v211 offset:8192
	s_waitcnt lgkmcnt(3)
	v_mfma_f32_32x32x16_bf16 v[64:79], v[238:241], v[116:119], v[64:79]
	v_add_u32_e32 v211, v209, v200
	ds_read_b128 v[238:241], v211 offset:8192
	s_waitcnt lgkmcnt(3)
	v_mfma_f32_32x32x16_bf16 v[64:79], v[242:245], v[112:115], v[64:79]
	v_add_u32_e32 v211, v209, v201
	ds_read_b128 v[242:245], v211 offset:8192
	s_waitcnt lgkmcnt(3)
	v_mfma_f32_32x32x16_bf16 v[64:79], v[230:233], v[108:111], v[64:79]
	v_add_u32_e32 v211, 0x6000, v203
	ds_read_b128 v[230:233], v211 offset:53248
	s_waitcnt lgkmcnt(3)
	v_mfma_f32_32x32x16_bf16 v[64:79], v[234:237], v[104:107], v[64:79]
	v_add_u32_e32 v211, 0x6000, v204
	ds_read_b128 v[234:237], v211 offset:53248
	s_waitcnt lgkmcnt(3)
	v_mfma_f32_32x32x16_bf16 v[64:79], v[238:241], v[100:103], v[64:79]
	v_add_u32_e32 v211, 0x6000, v205
	ds_read_b128 v[238:241], v211 offset:53248
	v_max_f32_e32 v249, v80, v81
	v_max3_f32 v249, v249, v82, v83
	s_waitcnt lgkmcnt(3)
	v_mfma_f32_32x32x16_bf16 v[64:79], v[242:245], v[96:99], v[64:79]
	v_add_u32_e32 v211, 0x6000, v206
	ds_read_b128 v[242:245], v211 offset:53248
	v_max3_f32 v249, v249, v84, v85
	v_max3_f32 v249, v249, v86, v87
	s_waitcnt lgkmcnt(3)
	v_mfma_f32_32x32x16_bf16 v[64:79], v[230:233], v[128:131], v[64:79]
	ds_read_b64_tr_b16 v[214:215], v185
	ds_read_b64_tr_b16 v[216:217], v185 offset:2048
	v_max3_f32 v249, v249, v88, v89
	v_max3_f32 v249, v249, v90, v91
	s_waitcnt lgkmcnt(4)
	v_mfma_f32_32x32x16_bf16 v[64:79], v[234:237], v[132:135], v[64:79]
	ds_read_b64_tr_b16 v[218:219], v185 offset:4096
	ds_read_b64_tr_b16 v[220:221], v185 offset:6144
	v_max3_f32 v249, v249, v92, v93
	v_max3_f32 v249, v249, v94, v95
	s_waitcnt lgkmcnt(5)
	v_mfma_f32_32x32x16_bf16 v[64:79], v[238:241], v[136:139], v[64:79]
	ds_read_b64_tr_b16 v[222:223], v185 offset:8192
	ds_read_b64_tr_b16 v[224:225], v185 offset:10240
	s_waitcnt lgkmcnt(6)
	v_mfma_f32_32x32x16_bf16 v[64:79], v[242:245], v[140:143], v[64:79]
	ds_read_b64_tr_b16 v[226:227], v185 offset:12288
	ds_read_b64_tr_b16 v[228:229], v185 offset:14336
	s_waitcnt lgkmcnt(6)
	v_mfma_f32_32x32x16_bf16 v[0:15], v[144:147], v[214:217], v[0:15]
	ds_read_b64_tr_b16 v[214:215], v185 offset:512
	ds_read_b64_tr_b16 v[216:217], v185 offset:2560
	s_waitcnt lgkmcnt(6)
	v_mfma_f32_32x32x16_bf16 v[0:15], v[148:151], v[218:221], v[0:15]
	ds_read_b64_tr_b16 v[218:219], v185 offset:4608
	ds_read_b64_tr_b16 v[220:221], v185 offset:6656
	s_waitcnt lgkmcnt(6)
	v_mfma_f32_32x32x16_bf16 v[0:15], v[152:155], v[222:225], v[0:15]
	ds_read_b64_tr_b16 v[222:223], v185 offset:8704
	ds_read_b64_tr_b16 v[224:225], v185 offset:10752
	s_waitcnt lgkmcnt(6)
	v_mfma_f32_32x32x16_bf16 v[0:15], v[156:159], v[226:229], v[0:15]
	ds_read_b64_tr_b16 v[226:227], v185 offset:12800
	ds_read_b64_tr_b16 v[228:229], v185 offset:14848
	s_waitcnt lgkmcnt(6)
	v_mfma_f32_32x32x16_bf16 v[48:63], v[144:147], v[214:217], v[48:63]
	ds_read_b64_tr_b16 v[214:215], v185 offset:1024
	ds_read_b64_tr_b16 v[216:217], v185 offset:3072
	v_max3_f32 v249, v249, v64, v65
	v_max3_f32 v249, v249, v66, v67
	v_max3_f32 v249, v249, v68, v69
	v_max3_f32 v249, v249, v70, v71
	v_max3_f32 v249, v249, v72, v73
	v_max3_f32 v249, v249, v74, v75
	v_max3_f32 v249, v249, v76, v77
	v_max3_f32 v249, v249, v78, v79
	s_waitcnt lgkmcnt(6)
	v_mfma_f32_32x32x16_bf16 v[48:63], v[148:151], v[218:221], v[48:63]
	ds_read_b64_tr_b16 v[218:219], v185 offset:5120
	ds_read_b64_tr_b16 v[220:221], v185 offset:7168
	v_mov_b32_e32 v250, v249
	s_nop 1
	v_permlane32_swap_b32_e32 v249, v250
	v_max_f32_e32 v249, v249, v250
	v_sub_f32_e32 v250, v249, v208
	v_cmp_ge_f32_e32 vcc, s40, v250
	v_max_f32_e32 v249, v208, v249
	v_sub_f32_e32 v250, v208, v249
	s_waitcnt lgkmcnt(6)
	v_mfma_f32_32x32x16_bf16 v[48:63], v[152:155], v[222:225], v[48:63]
	ds_read_b64_tr_b16 v[222:223], v185 offset:9216
	ds_read_b64_tr_b16 v[224:225], v185 offset:11264
	v_mul_f32_e32 v250, 0x3dd53b94, v250
	v_exp_f32_e32 v250, v250
	s_cmp_eq_u64 vcc, exec
	s_cselect_b64 s[10:11], -1, 0
	v_cndmask_b32_e64 v207, v250, 1.0, s[10:11]
	v_cndmask_b32_e64 v208, v249, v208, s[10:11]
	v_mul_f32_e32 v251, 0xbdd53b94, v208
	v_fmamk_f32 v80, v80, 0x3dd53b94, v251
	s_waitcnt lgkmcnt(6)
	v_mfma_f32_32x32x16_bf16 v[48:63], v[156:159], v[226:229], v[48:63]
	ds_read_b64_tr_b16 v[226:227], v185 offset:13312
	ds_read_b64_tr_b16 v[228:229], v185 offset:15360
	v_fmamk_f32 v81, v81, 0x3dd53b94, v251
	v_fmamk_f32 v82, v82, 0x3dd53b94, v251
	v_fmamk_f32 v83, v83, 0x3dd53b94, v251
	v_fmamk_f32 v84, v84, 0x3dd53b94, v251
	v_fmamk_f32 v85, v85, 0x3dd53b94, v251
	v_fmamk_f32 v86, v86, 0x3dd53b94, v251
	v_fmamk_f32 v87, v87, 0x3dd53b94, v251
	s_waitcnt lgkmcnt(6)
	v_mfma_f32_32x32x16_bf16 v[32:47], v[144:147], v[214:217], v[32:47]
	ds_read_b64_tr_b16 v[214:215], v185 offset:1536
	ds_read_b64_tr_b16 v[216:217], v185 offset:3584
	v_fmamk_f32 v88, v88, 0x3dd53b94, v251
	v_fmamk_f32 v89, v89, 0x3dd53b94, v251
	v_fmamk_f32 v90, v90, 0x3dd53b94, v251
	v_fmamk_f32 v91, v91, 0x3dd53b94, v251
	v_fmamk_f32 v92, v92, 0x3dd53b94, v251
	v_fmamk_f32 v93, v93, 0x3dd53b94, v251
	v_fmamk_f32 v94, v94, 0x3dd53b94, v251
	s_waitcnt lgkmcnt(6)
	v_mfma_f32_32x32x16_bf16 v[32:47], v[148:151], v[218:221], v[32:47]
	ds_read_b64_tr_b16 v[218:219], v185 offset:5632
	ds_read_b64_tr_b16 v[220:221], v185 offset:7680
	v_fmamk_f32 v95, v95, 0x3dd53b94, v251
	v_exp_f32_e32 v80, v80
	v_fmamk_f32 v64, v64, 0x3dd53b94, v251
	v_exp_f32_e32 v81, v81
	v_fmamk_f32 v65, v65, 0x3dd53b94, v251
	v_add_f32_e32 v212, 0, v80
	v_exp_f32_e32 v82, v82
	s_waitcnt lgkmcnt(6)
	v_mfma_f32_32x32x16_bf16 v[32:47], v[152:155], v[222:225], v[32:47]
	ds_read_b64_tr_b16 v[222:223], v185 offset:9728
	ds_read_b64_tr_b16 v[224:225], v185 offset:11776
	v_fmamk_f32 v66, v66, 0x3dd53b94, v251
	v_add_f32_e32 v212, v81, v212
	v_exp_f32_e32 v83, v83
	v_fmamk_f32 v67, v67, 0x3dd53b94, v251
	v_add_f32_e32 v212, v82, v212
	v_exp_f32_e32 v84, v84
	v_fmamk_f32 v68, v68, 0x3dd53b94, v251
	s_waitcnt lgkmcnt(6)
	v_mfma_f32_32x32x16_bf16 v[32:47], v[156:159], v[226:229], v[32:47]
	ds_read_b64_tr_b16 v[226:227], v185 offset:13824
	ds_read_b64_tr_b16 v[228:229], v185 offset:15872
	v_add_f32_e32 v212, v83, v212
	v_exp_f32_e32 v85, v85
	v_fmamk_f32 v69, v69, 0x3dd53b94, v251
	v_add_f32_e32 v212, v84, v212
	v_exp_f32_e32 v86, v86
	v_fmamk_f32 v70, v70, 0x3dd53b94, v251
	v_add_f32_e32 v212, v85, v212
	s_waitcnt lgkmcnt(6)
	v_mfma_f32_32x32x16_bf16 v[16:31], v[144:147], v[214:217], v[16:31]
	v_exp_f32_e32 v87, v87
	v_fmamk_f32 v71, v71, 0x3dd53b94, v251
	v_add_f32_e32 v212, v86, v212
	v_exp_f32_e32 v88, v88
	v_fmamk_f32 v72, v72, 0x3dd53b94, v251
	v_add_f32_e32 v212, v87, v212
	v_exp_f32_e32 v89, v89
	s_waitcnt lgkmcnt(4)
	v_mfma_f32_32x32x16_bf16 v[16:31], v[148:151], v[218:221], v[16:31]
	v_fmamk_f32 v73, v73, 0x3dd53b94, v251
	v_add_f32_e32 v212, v88, v212
	v_exp_f32_e32 v90, v90
	v_fmamk_f32 v74, v74, 0x3dd53b94, v251
	v_add_f32_e32 v212, v89, v212
	v_exp_f32_e32 v91, v91
	v_fmamk_f32 v75, v75, 0x3dd53b94, v251
	s_waitcnt lgkmcnt(2)
	v_mfma_f32_32x32x16_bf16 v[16:31], v[152:155], v[222:225], v[16:31]
	v_add_f32_e32 v212, v90, v212
	v_exp_f32_e32 v92, v92
	v_fmamk_f32 v76, v76, 0x3dd53b94, v251
	v_add_f32_e32 v212, v91, v212
	v_exp_f32_e32 v93, v93
	v_fmamk_f32 v77, v77, 0x3dd53b94, v251
	v_add_f32_e32 v212, v92, v212
	s_waitcnt lgkmcnt(0)
	v_mfma_f32_32x32x16_bf16 v[16:31], v[156:159], v[226:229], v[16:31]
	v_exp_f32_e32 v94, v94
	v_fmamk_f32 v78, v78, 0x3dd53b94, v251
	v_add_f32_e32 v212, v93, v212
	v_exp_f32_e32 v95, v95
	v_fmamk_f32 v79, v79, 0x3dd53b94, v251
	v_add_f32_e32 v212, v94, v212
	v_add_f32_e32 v212, v95, v212
	v_cvt_pk_bf16_f32 v144, v80, v81
	v_cvt_pk_bf16_f32 v145, v82, v83
	v_cvt_pk_bf16_f32 v146, v84, v85
	v_cvt_pk_bf16_f32 v147, v86, v87
	v_cvt_pk_bf16_f32 v148, v88, v89
	v_cvt_pk_bf16_f32 v149, v90, v91
	v_cvt_pk_bf16_f32 v150, v92, v93
	v_cvt_pk_bf16_f32 v151, v94, v95
	v_permlane32_swap_b32_e32 v144, v146
	v_permlane32_swap_b32_e32 v145, v147
	v_permlane32_swap_b32_e32 v148, v150
	v_permlane32_swap_b32_e32 v149, v151
	v_cmp_gt_f32_e32 vcc, 1.0, v207
	s_cbranch_vccz .Lmla_noresc_o
	s_and_saveexec_b64 s[0:1], s[8:9]
	ds_write_b32 v182, v207 offset:128
	s_or_b64 exec, exec, s[0:1]
	s_waitcnt lgkmcnt(0)
	v_add_u32_e32 v253, s50, v181
	ds_read_b128 v[92:95], v253 offset:224
	ds_read_b128 v[88:91], v253 offset:192
	ds_read_b128 v[84:87], v253 offset:160
	ds_read_b128 v[80:83], v253 offset:128
	s_waitcnt lgkmcnt(3)
	v_pk_mul_f32 v[12:13], v[12:13], v[92:93]
	v_pk_mul_f32 v[14:15], v[14:15], v[94:95]
	v_pk_mul_f32 v[60:61], v[60:61], v[92:93]
	v_pk_mul_f32 v[62:63], v[62:63], v[94:95]
	v_pk_mul_f32 v[44:45], v[44:45], v[92:93]
	v_pk_mul_f32 v[46:47], v[46:47], v[94:95]
	v_pk_mul_f32 v[28:29], v[28:29], v[92:93]
	v_pk_mul_f32 v[30:31], v[30:31], v[94:95]
	s_waitcnt lgkmcnt(2)
	v_pk_mul_f32 v[8:9], v[8:9], v[88:89]
	v_pk_mul_f32 v[10:11], v[10:11], v[90:91]
	v_pk_mul_f32 v[56:57], v[56:57], v[88:89]
	v_pk_mul_f32 v[58:59], v[58:59], v[90:91]
	v_pk_mul_f32 v[40:41], v[40:41], v[88:89]
	v_pk_mul_f32 v[42:43], v[42:43], v[90:91]
	v_pk_mul_f32 v[24:25], v[24:25], v[88:89]
	v_pk_mul_f32 v[26:27], v[26:27], v[90:91]
	s_waitcnt lgkmcnt(1)
	v_pk_mul_f32 v[4:5], v[4:5], v[84:85]
	v_pk_mul_f32 v[6:7], v[6:7], v[86:87]
	v_pk_mul_f32 v[52:53], v[52:53], v[84:85]
	v_pk_mul_f32 v[54:55], v[54:55], v[86:87]
	v_pk_mul_f32 v[36:37], v[36:37], v[84:85]
	v_pk_mul_f32 v[38:39], v[38:39], v[86:87]
	v_pk_mul_f32 v[20:21], v[20:21], v[84:85]
	v_pk_mul_f32 v[22:23], v[22:23], v[86:87]
	s_waitcnt lgkmcnt(0)
	v_pk_mul_f32 v[0:1], v[0:1], v[80:81]
	v_pk_mul_f32 v[2:3], v[2:3], v[82:83]
	v_pk_mul_f32 v[48:49], v[48:49], v[80:81]
	v_pk_mul_f32 v[50:51], v[50:51], v[82:83]
	v_pk_mul_f32 v[32:33], v[32:33], v[80:81]
	v_pk_mul_f32 v[34:35], v[34:35], v[82:83]
	v_pk_mul_f32 v[16:17], v[16:17], v[80:81]
	v_pk_mul_f32 v[18:19], v[18:19], v[82:83]
.Lmla_noresc_o:
	s_add_i32 s58, s58, 1
	s_waitcnt vmcnt(0) lgkmcnt(0)
	s_barrier
	ds_read_b128 v[230:233], v193 offset:32768
	ds_read_b128 v[234:237], v186 offset:32768
	ds_read_b128 v[238:241], v187 offset:32768
	ds_read_b128 v[242:245], v188 offset:32768
	s_cmp_lt_u32 s58, s18
	s_cselect_b32 s0, 0, s18
	s_cselect_b32 s1, s6, s13
	s_lshl_b32 s0, s0, 6
	s_sub_i32 s0, s1, s0
	s_add_i32 s0, s51, s0
	s_add_i32 s0, s0, 64
	s_ashr_i32 s1, s0, 31
	s_lshl_b64 s[10:11], s[0:1], 12
	s_add_u32 s16, s20, s10
	s_addc_u32 s17, s21, s11
	v_exp_f32_e32 v64, v64
	v_exp_f32_e32 v65, v65
	v_add_f32_e32 v212, v64, v212
	v_exp_f32_e32 v66, v66
	v_add_f32_e32 v212, v65, v212
	v_exp_f32_e32 v67, v67
	s_waitcnt lgkmcnt(3)
	v_mfma_f32_32x32x16_bf16 v[80:95], v[230:233], v[124:127], 0
	ds_read_b128 v[230:233], v189 offset:32768
	s_mov_b32 m0, s22
	v_lshl_add_u64 v[254:255], v[164:165], 1, s[100:101]
	global_load_lds_dwordx4 v[254:255], off
	v_add_f32_e32 v212, v66, v212
	v_exp_f32_e32 v68, v68
	v_add_f32_e32 v212, v67, v212
	v_exp_f32_e32 v69, v69
	s_waitcnt lgkmcnt(3)
	v_mfma_f32_32x32x16_bf16 v[80:95], v[234:237], v[120:123], v[80:95]
	ds_read_b128 v[234:237], v190 offset:32768
	s_mov_b32 m0, s31
	v_lshl_add_u64 v[254:255], v[166:167], 1, s[100:101]
	global_load_lds_dwordx4 v[254:255], off
	v_add_f32_e32 v212, v68, v212
	v_exp_f32_e32 v70, v70
	v_add_f32_e32 v212, v69, v212
	v_exp_f32_e32 v71, v71
	s_waitcnt lgkmcnt(3)
	v_mfma_f32_32x32x16_bf16 v[80:95], v[238:241], v[116:119], v[80:95]
	ds_read_b128 v[238:241], v191 offset:32768
	v_add_f32_e32 v212, v70, v212
	v_exp_f32_e32 v72, v72
	v_add_f32_e32 v212, v71, v212
	v_exp_f32_e32 v73, v73
	s_waitcnt lgkmcnt(3)
	v_mfma_f32_32x32x16_bf16 v[80:95], v[242:245], v[112:115], v[80:95]
	ds_read_b128 v[242:245], v192 offset:32768
	s_mov_b32 m0, s44
	v_lshl_add_u64 v[254:255], v[160:161], 1, s[16:17]
	global_load_lds_dwordx4 v[254:255], off
	v_add_f32_e32 v212, v72, v212
	v_exp_f32_e32 v74, v74
	v_add_f32_e32 v212, v73, v212
	v_exp_f32_e32 v75, v75
	s_waitcnt lgkmcnt(3)
	v_mfma_f32_32x32x16_bf16 v[80:95], v[230:233], v[108:111], v[80:95]
	ds_read_b128 v[230:233], v203 offset:49152
	v_add_f32_e32 v212, v74, v212
	v_exp_f32_e32 v76, v76
	v_add_f32_e32 v212, v75, v212
	v_exp_f32_e32 v77, v77
	s_waitcnt lgkmcnt(3)
	v_mfma_f32_32x32x16_bf16 v[80:95], v[234:237], v[104:107], v[80:95]
	ds_read_b128 v[234:237], v204 offset:49152
	s_mov_b32 m0, s45
	v_lshl_add_u64 v[254:255], v[162:163], 1, s[16:17]
	global_load_lds_dwordx4 v[254:255], off
	v_add_f32_e32 v212, v76, v212
	v_exp_f32_e32 v78, v78
	v_add_f32_e32 v212, v77, v212
	v_exp_f32_e32 v79, v79
	s_waitcnt lgkmcnt(3)
	v_mfma_f32_32x32x16_bf16 v[80:95], v[238:241], v[100:103], v[80:95]
	ds_read_b128 v[238:241], v205 offset:49152
	v_add_f32_e32 v212, v78, v212
	v_add_f32_e32 v212, v79, v212
	v_mov_b32_e32 v213, v212
	s_waitcnt lgkmcnt(3)
	v_mfma_f32_32x32x16_bf16 v[80:95], v[242:245], v[96:99], v[80:95]
	ds_read_b128 v[242:245], v206 offset:49152
	s_mov_b32 m0, s49
	v_mad_i64_i32 v[254:255], s[0:1], s0, v180, v[168:169]
	global_load_lds_dwordx4 v[254:255], off
	s_add_u32 s100, s16, 0x100
	s_addc_u32 s101, s17, 0
	v_cvt_pk_bf16_f32 v152, v64, v65
	v_cvt_pk_bf16_f32 v153, v66, v67
	v_cvt_pk_bf16_f32 v154, v68, v69
	s_waitcnt lgkmcnt(3)
	v_mfma_f32_32x32x16_bf16 v[80:95], v[230:233], v[128:131], v[80:95]
	ds_read_b128 v[230:233], v193 offset:40960
	v_cvt_pk_bf16_f32 v155, v70, v71
	v_cvt_pk_bf16_f32 v156, v72, v73
	v_cvt_pk_bf16_f32 v157, v74, v75
	s_waitcnt lgkmcnt(3)
	v_mfma_f32_32x32x16_bf16 v[80:95], v[234:237], v[132:135], v[80:95]
	ds_read_b128 v[234:237], v186 offset:40960
	v_cvt_pk_bf16_f32 v158, v76, v77
	v_cvt_pk_bf16_f32 v159, v78, v79
	v_permlane32_swap_b32_e32 v212, v213
	s_waitcnt lgkmcnt(3)
	v_mfma_f32_32x32x16_bf16 v[80:95], v[238:241], v[136:139], v[80:95]
	ds_read_b128 v[238:241], v187 offset:40960
	v_add_f32_e32 v252, v212, v213
	v_fma_f32 v183, v207, v183, v252
	v_permlane32_swap_b32_e32 v152, v154
	s_waitcnt lgkmcnt(3)
	v_mfma_f32_32x32x16_bf16 v[80:95], v[242:245], v[140:143], v[80:95]
	ds_read_b128 v[242:245], v188 offset:40960
	v_permlane32_swap_b32_e32 v153, v155
	v_permlane32_swap_b32_e32 v156, v158
	v_permlane32_swap_b32_e32 v157, v159
	s_waitcnt lgkmcnt(3)
	v_mfma_f32_32x32x16_bf16 v[64:79], v[230:233], v[124:127], 0
	ds_read_b128 v[230:233], v189 offset:40960
	s_waitcnt lgkmcnt(3)
	v_mfma_f32_32x32x16_bf16 v[64:79], v[234:237], v[120:123], v[64:79]
	ds_read_b128 v[234:237], v190 offset:40960
	s_waitcnt lgkmcnt(3)
	v_mfma_f32_32x32x16_bf16 v[64:79], v[238:241], v[116:119], v[64:79]
	ds_read_b128 v[238:241], v191 offset:40960
	s_waitcnt lgkmcnt(3)
	v_mfma_f32_32x32x16_bf16 v[64:79], v[242:245], v[112:115], v[64:79]
	ds_read_b128 v[242:245], v192 offset:40960
	s_waitcnt lgkmcnt(3)
	v_mfma_f32_32x32x16_bf16 v[64:79], v[230:233], v[108:111], v[64:79]
	ds_read_b128 v[230:233], v203 offset:53248
	s_waitcnt lgkmcnt(3)
	v_mfma_f32_32x32x16_bf16 v[64:79], v[234:237], v[104:107], v[64:79]
	ds_read_b128 v[234:237], v204 offset:53248
	s_waitcnt lgkmcnt(3)
	v_mfma_f32_32x32x16_bf16 v[64:79], v[238:241], v[100:103], v[64:79]
	ds_read_b128 v[238:241], v205 offset:53248
	v_max_f32_e32 v249, v80, v81
	v_max3_f32 v249, v249, v82, v83
	s_waitcnt lgkmcnt(3)
	v_mfma_f32_32x32x16_bf16 v[64:79], v[242:245], v[96:99], v[64:79]
	ds_read_b128 v[242:245], v206 offset:53248
	v_max3_f32 v249, v249, v84, v85
	v_max3_f32 v249, v249, v86, v87
	s_waitcnt lgkmcnt(3)
	v_mfma_f32_32x32x16_bf16 v[64:79], v[230:233], v[128:131], v[64:79]
	ds_read_b64_tr_b16 v[214:215], v184
	ds_read_b64_tr_b16 v[216:217], v184 offset:2048
	v_max3_f32 v249, v249, v88, v89
	v_max3_f32 v249, v249, v90, v91
	s_waitcnt lgkmcnt(4)
	v_mfma_f32_32x32x16_bf16 v[64:79], v[234:237], v[132:135], v[64:79]
	ds_read_b64_tr_b16 v[218:219], v184 offset:4096
	ds_read_b64_tr_b16 v[220:221], v184 offset:6144
	v_max3_f32 v249, v249, v92, v93
	v_max3_f32 v249, v249, v94, v95
	s_waitcnt lgkmcnt(5)
	v_mfma_f32_32x32x16_bf16 v[64:79], v[238:241], v[136:139], v[64:79]
	ds_read_b64_tr_b16 v[222:223], v184 offset:8192
	ds_read_b64_tr_b16 v[224:225], v184 offset:10240
	s_waitcnt lgkmcnt(6)
	v_mfma_f32_32x32x16_bf16 v[64:79], v[242:245], v[140:143], v[64:79]
	ds_read_b64_tr_b16 v[226:227], v184 offset:12288
	ds_read_b64_tr_b16 v[228:229], v184 offset:14336
	s_waitcnt lgkmcnt(6)
	v_mfma_f32_32x32x16_bf16 v[0:15], v[144:147], v[214:217], v[0:15]
	ds_read_b64_tr_b16 v[214:215], v184 offset:512
	ds_read_b64_tr_b16 v[216:217], v184 offset:2560
	s_waitcnt lgkmcnt(6)
	v_mfma_f32_32x32x16_bf16 v[0:15], v[148:151], v[218:221], v[0:15]
	ds_read_b64_tr_b16 v[218:219], v184 offset:4608
	ds_read_b64_tr_b16 v[220:221], v184 offset:6656
	s_waitcnt lgkmcnt(6)
	v_mfma_f32_32x32x16_bf16 v[0:15], v[152:155], v[222:225], v[0:15]
	ds_read_b64_tr_b16 v[222:223], v184 offset:8704
	ds_read_b64_tr_b16 v[224:225], v184 offset:10752
	s_waitcnt lgkmcnt(6)
	v_mfma_f32_32x32x16_bf16 v[0:15], v[156:159], v[226:229], v[0:15]
	ds_read_b64_tr_b16 v[226:227], v184 offset:12800
	ds_read_b64_tr_b16 v[228:229], v184 offset:14848
	s_waitcnt lgkmcnt(6)
	v_mfma_f32_32x32x16_bf16 v[48:63], v[144:147], v[214:217], v[48:63]
	ds_read_b64_tr_b16 v[214:215], v184 offset:1024
	ds_read_b64_tr_b16 v[216:217], v184 offset:3072
	v_max3_f32 v249, v249, v64, v65
	v_max3_f32 v249, v249, v66, v67
	v_max3_f32 v249, v249, v68, v69
	v_max3_f32 v249, v249, v70, v71
	v_max3_f32 v249, v249, v72, v73
	v_max3_f32 v249, v249, v74, v75
	v_max3_f32 v249, v249, v76, v77
	v_max3_f32 v249, v249, v78, v79
	s_waitcnt lgkmcnt(6)
	v_mfma_f32_32x32x16_bf16 v[48:63], v[148:151], v[218:221], v[48:63]
	ds_read_b64_tr_b16 v[218:219], v184 offset:5120
	ds_read_b64_tr_b16 v[220:221], v184 offset:7168
	v_mov_b32_e32 v250, v249
	s_nop 1
	v_permlane32_swap_b32_e32 v249, v250
	v_max_f32_e32 v249, v249, v250
	v_sub_f32_e32 v250, v249, v208
	v_cmp_ge_f32_e32 vcc, s40, v250
	v_max_f32_e32 v249, v208, v249
	v_sub_f32_e32 v250, v208, v249
	s_waitcnt lgkmcnt(6)
	v_mfma_f32_32x32x16_bf16 v[48:63], v[152:155], v[222:225], v[48:63]
	ds_read_b64_tr_b16 v[222:223], v184 offset:9216
	ds_read_b64_tr_b16 v[224:225], v184 offset:11264
	v_mul_f32_e32 v250, 0x3dd53b94, v250
	v_exp_f32_e32 v250, v250
	s_cmp_eq_u64 vcc, exec
	s_cselect_b64 s[10:11], -1, 0
	v_cndmask_b32_e64 v207, v250, 1.0, s[10:11]
	v_cndmask_b32_e64 v208, v249, v208, s[10:11]
	v_mul_f32_e32 v251, 0xbdd53b94, v208
	v_fmamk_f32 v80, v80, 0x3dd53b94, v251
	s_waitcnt lgkmcnt(6)
	v_mfma_f32_32x32x16_bf16 v[48:63], v[156:159], v[226:229], v[48:63]
	ds_read_b64_tr_b16 v[226:227], v184 offset:13312
	ds_read_b64_tr_b16 v[228:229], v184 offset:15360
	v_fmamk_f32 v81, v81, 0x3dd53b94, v251
	v_fmamk_f32 v82, v82, 0x3dd53b94, v251
	v_fmamk_f32 v83, v83, 0x3dd53b94, v251
	v_fmamk_f32 v84, v84, 0x3dd53b94, v251
	v_fmamk_f32 v85, v85, 0x3dd53b94, v251
	v_fmamk_f32 v86, v86, 0x3dd53b94, v251
	v_fmamk_f32 v87, v87, 0x3dd53b94, v251
	s_waitcnt lgkmcnt(6)
	v_mfma_f32_32x32x16_bf16 v[32:47], v[144:147], v[214:217], v[32:47]
	ds_read_b64_tr_b16 v[214:215], v184 offset:1536
	ds_read_b64_tr_b16 v[216:217], v184 offset:3584
	v_fmamk_f32 v88, v88, 0x3dd53b94, v251
	v_fmamk_f32 v89, v89, 0x3dd53b94, v251
	v_fmamk_f32 v90, v90, 0x3dd53b94, v251
	v_fmamk_f32 v91, v91, 0x3dd53b94, v251
	v_fmamk_f32 v92, v92, 0x3dd53b94, v251
	v_fmamk_f32 v93, v93, 0x3dd53b94, v251
	v_fmamk_f32 v94, v94, 0x3dd53b94, v251
	s_waitcnt lgkmcnt(6)
	v_mfma_f32_32x32x16_bf16 v[32:47], v[148:151], v[218:221], v[32:47]
	ds_read_b64_tr_b16 v[218:219], v184 offset:5632
	ds_read_b64_tr_b16 v[220:221], v184 offset:7680
	v_fmamk_f32 v95, v95, 0x3dd53b94, v251
	v_exp_f32_e32 v80, v80
	v_fmamk_f32 v64, v64, 0x3dd53b94, v251
	v_exp_f32_e32 v81, v81
	v_fmamk_f32 v65, v65, 0x3dd53b94, v251
	v_add_f32_e32 v212, 0, v80
	v_exp_f32_e32 v82, v82
	s_waitcnt lgkmcnt(6)
	v_mfma_f32_32x32x16_bf16 v[32:47], v[152:155], v[222:225], v[32:47]
	ds_read_b64_tr_b16 v[222:223], v184 offset:9728
	ds_read_b64_tr_b16 v[224:225], v184 offset:11776
	v_fmamk_f32 v66, v66, 0x3dd53b94, v251
	v_add_f32_e32 v212, v81, v212
	v_exp_f32_e32 v83, v83
	v_fmamk_f32 v67, v67, 0x3dd53b94, v251
	v_add_f32_e32 v212, v82, v212
	v_exp_f32_e32 v84, v84
	v_fmamk_f32 v68, v68, 0x3dd53b94, v251
	s_waitcnt lgkmcnt(6)
	v_mfma_f32_32x32x16_bf16 v[32:47], v[156:159], v[226:229], v[32:47]
	ds_read_b64_tr_b16 v[226:227], v184 offset:13824
	ds_read_b64_tr_b16 v[228:229], v184 offset:15872
	v_add_f32_e32 v212, v83, v212
	v_exp_f32_e32 v85, v85
	v_fmamk_f32 v69, v69, 0x3dd53b94, v251
	v_add_f32_e32 v212, v84, v212
	v_exp_f32_e32 v86, v86
	v_fmamk_f32 v70, v70, 0x3dd53b94, v251
	v_add_f32_e32 v212, v85, v212
	s_waitcnt lgkmcnt(6)
	v_mfma_f32_32x32x16_bf16 v[16:31], v[144:147], v[214:217], v[16:31]
	v_exp_f32_e32 v87, v87
	v_fmamk_f32 v71, v71, 0x3dd53b94, v251
	v_add_f32_e32 v212, v86, v212
	v_exp_f32_e32 v88, v88
	v_fmamk_f32 v72, v72, 0x3dd53b94, v251
	v_add_f32_e32 v212, v87, v212
	v_exp_f32_e32 v89, v89
	s_waitcnt lgkmcnt(4)
	v_mfma_f32_32x32x16_bf16 v[16:31], v[148:151], v[218:221], v[16:31]
	v_fmamk_f32 v73, v73, 0x3dd53b94, v251
	v_add_f32_e32 v212, v88, v212
	v_exp_f32_e32 v90, v90
	v_fmamk_f32 v74, v74, 0x3dd53b94, v251
	v_add_f32_e32 v212, v89, v212
	v_exp_f32_e32 v91, v91
	v_fmamk_f32 v75, v75, 0x3dd53b94, v251
	s_waitcnt lgkmcnt(2)
	v_mfma_f32_32x32x16_bf16 v[16:31], v[152:155], v[222:225], v[16:31]
	v_add_f32_e32 v212, v90, v212
	v_exp_f32_e32 v92, v92
	v_fmamk_f32 v76, v76, 0x3dd53b94, v251
	v_add_f32_e32 v212, v91, v212
	v_exp_f32_e32 v93, v93
	v_fmamk_f32 v77, v77, 0x3dd53b94, v251
	v_add_f32_e32 v212, v92, v212
	s_waitcnt lgkmcnt(0)
	v_mfma_f32_32x32x16_bf16 v[16:31], v[156:159], v[226:229], v[16:31]
	v_exp_f32_e32 v94, v94
	v_fmamk_f32 v78, v78, 0x3dd53b94, v251
	v_add_f32_e32 v212, v93, v212
	v_exp_f32_e32 v95, v95
	v_fmamk_f32 v79, v79, 0x3dd53b94, v251
	v_add_f32_e32 v212, v94, v212
	v_add_f32_e32 v212, v95, v212
	v_cvt_pk_bf16_f32 v144, v80, v81
	v_cvt_pk_bf16_f32 v145, v82, v83
	v_cvt_pk_bf16_f32 v146, v84, v85
	v_cvt_pk_bf16_f32 v147, v86, v87
	v_cvt_pk_bf16_f32 v148, v88, v89
	v_cvt_pk_bf16_f32 v149, v90, v91
	v_cvt_pk_bf16_f32 v150, v92, v93
	v_cvt_pk_bf16_f32 v151, v94, v95
	v_permlane32_swap_b32_e32 v144, v146
	v_permlane32_swap_b32_e32 v145, v147
	v_permlane32_swap_b32_e32 v148, v150
	v_permlane32_swap_b32_e32 v149, v151
	v_cmp_gt_f32_e32 vcc, 1.0, v207
	s_cbranch_vccz .Lmla_noresc_e
	s_and_saveexec_b64 s[0:1], s[8:9]
	ds_write_b32 v182, v207 offset:128
	s_or_b64 exec, exec, s[0:1]
	s_waitcnt lgkmcnt(0)
	v_add_u32_e32 v253, s50, v181
	ds_read_b128 v[92:95], v253 offset:224
	ds_read_b128 v[88:91], v253 offset:192
	ds_read_b128 v[84:87], v253 offset:160
	ds_read_b128 v[80:83], v253 offset:128
	s_waitcnt lgkmcnt(3)
	v_pk_mul_f32 v[12:13], v[12:13], v[92:93]
	v_pk_mul_f32 v[14:15], v[14:15], v[94:95]
	v_pk_mul_f32 v[60:61], v[60:61], v[92:93]
	v_pk_mul_f32 v[62:63], v[62:63], v[94:95]
	v_pk_mul_f32 v[44:45], v[44:45], v[92:93]
	v_pk_mul_f32 v[46:47], v[46:47], v[94:95]
	v_pk_mul_f32 v[28:29], v[28:29], v[92:93]
	v_pk_mul_f32 v[30:31], v[30:31], v[94:95]
	s_waitcnt lgkmcnt(2)
	v_pk_mul_f32 v[8:9], v[8:9], v[88:89]
	v_pk_mul_f32 v[10:11], v[10:11], v[90:91]
	v_pk_mul_f32 v[56:57], v[56:57], v[88:89]
	v_pk_mul_f32 v[58:59], v[58:59], v[90:91]
	v_pk_mul_f32 v[40:41], v[40:41], v[88:89]
	v_pk_mul_f32 v[42:43], v[42:43], v[90:91]
	v_pk_mul_f32 v[24:25], v[24:25], v[88:89]
	v_pk_mul_f32 v[26:27], v[26:27], v[90:91]
	s_waitcnt lgkmcnt(1)
	v_pk_mul_f32 v[4:5], v[4:5], v[84:85]
	v_pk_mul_f32 v[6:7], v[6:7], v[86:87]
	v_pk_mul_f32 v[52:53], v[52:53], v[84:85]
	v_pk_mul_f32 v[54:55], v[54:55], v[86:87]
	v_pk_mul_f32 v[36:37], v[36:37], v[84:85]
	v_pk_mul_f32 v[38:39], v[38:39], v[86:87]
	v_pk_mul_f32 v[20:21], v[20:21], v[84:85]
	v_pk_mul_f32 v[22:23], v[22:23], v[86:87]
	s_waitcnt lgkmcnt(0)
	v_pk_mul_f32 v[0:1], v[0:1], v[80:81]
	v_pk_mul_f32 v[2:3], v[2:3], v[82:83]
	v_pk_mul_f32 v[48:49], v[48:49], v[80:81]
	v_pk_mul_f32 v[50:51], v[50:51], v[82:83]
	v_pk_mul_f32 v[32:33], v[32:33], v[80:81]
	v_pk_mul_f32 v[34:35], v[34:35], v[82:83]
	v_pk_mul_f32 v[16:17], v[16:17], v[80:81]
	v_pk_mul_f32 v[18:19], v[18:19], v[82:83]
.Lmla_noresc_e:
	s_add_i32 s58, s58, 1
	s_addk_i32 s51, 0x80
	s_waitcnt vmcnt(0) lgkmcnt(0)
	s_barrier
	s_cmp_ge_u32 s58, s19
	s_cbranch_scc0 .Lmla_loop
	ds_read_b128 v[230:233], v193 offset:57344
	ds_read_b128 v[234:237], v186 offset:57344
	ds_read_b128 v[238:241], v187 offset:57344
	ds_read_b128 v[242:245], v188 offset:57344
	v_exp_f32_e32 v64, v64
	v_exp_f32_e32 v65, v65
	v_add_f32_e32 v212, v64, v212
	v_exp_f32_e32 v66, v66
	v_add_f32_e32 v212, v65, v212
	v_exp_f32_e32 v67, v67
	s_waitcnt lgkmcnt(3)
	v_mfma_f32_32x32x16_bf16 v[80:95], v[230:233], v[124:127], 0
	ds_read_b128 v[230:233], v189 offset:57344
	s_mov_b32 m0, s54
	v_lshl_add_u64 v[254:255], v[164:165], 1, s[100:101]
	global_load_lds_dwordx4 v[254:255], off
	v_add_f32_e32 v212, v66, v212
	v_exp_f32_e32 v68, v68
	v_add_f32_e32 v212, v67, v212
	v_exp_f32_e32 v69, v69
	s_waitcnt lgkmcnt(3)
	v_mfma_f32_32x32x16_bf16 v[80:95], v[234:237], v[120:123], v[80:95]
	ds_read_b128 v[234:237], v190 offset:57344
	s_mov_b32 m0, s55
	v_lshl_add_u64 v[254:255], v[166:167], 1, s[100:101]
	global_load_lds_dwordx4 v[254:255], off
	v_add_f32_e32 v212, v68, v212
	v_exp_f32_e32 v70, v70
	v_add_f32_e32 v212, v69, v212
	v_exp_f32_e32 v71, v71
	s_waitcnt lgkmcnt(3)
	v_mfma_f32_32x32x16_bf16 v[80:95], v[238:241], v[116:119], v[80:95]
	ds_read_b128 v[238:241], v191 offset:57344
	v_add_f32_e32 v212, v70, v212
	v_exp_f32_e32 v72, v72
	v_add_f32_e32 v212, v71, v212
	v_exp_f32_e32 v73, v73
	s_waitcnt lgkmcnt(3)
	v_mfma_f32_32x32x16_bf16 v[80:95], v[242:245], v[112:115], v[80:95]
	ds_read_b128 v[242:245], v192 offset:57344
	v_add_f32_e32 v212, v72, v212
	v_exp_f32_e32 v74, v74
	v_add_f32_e32 v212, v73, v212
	v_exp_f32_e32 v75, v75
	s_waitcnt lgkmcnt(3)
	v_mfma_f32_32x32x16_bf16 v[80:95], v[230:233], v[108:111], v[80:95]
	v_add_u32_e32 v211, 0x6000, v203
	ds_read_b128 v[230:233], v211 offset:49152
	v_add_f32_e32 v212, v74, v212
	v_exp_f32_e32 v76, v76
	v_add_f32_e32 v212, v75, v212
	v_exp_f32_e32 v77, v77
	s_waitcnt lgkmcnt(3)
	v_mfma_f32_32x32x16_bf16 v[80:95], v[234:237], v[104:107], v[80:95]
	v_add_u32_e32 v211, 0x6000, v204
	ds_read_b128 v[234:237], v211 offset:49152
	v_add_f32_e32 v212, v76, v212
	v_exp_f32_e32 v78, v78
	v_add_f32_e32 v212, v77, v212
	v_exp_f32_e32 v79, v79
	s_waitcnt lgkmcnt(3)
	v_mfma_f32_32x32x16_bf16 v[80:95], v[238:241], v[100:103], v[80:95]
	v_add_u32_e32 v211, 0x6000, v205
	ds_read_b128 v[238:241], v211 offset:49152
	v_add_f32_e32 v212, v78, v212
	v_add_f32_e32 v212, v79, v212
	v_mov_b32_e32 v213, v212
	s_waitcnt lgkmcnt(3)
	v_mfma_f32_32x32x16_bf16 v[80:95], v[242:245], v[96:99], v[80:95]
	v_add_u32_e32 v211, 0x6000, v206
	ds_read_b128 v[242:245], v211 offset:49152
	v_cvt_pk_bf16_f32 v152, v64, v65
	v_cvt_pk_bf16_f32 v153, v66, v67
	v_cvt_pk_bf16_f32 v154, v68, v69
	s_waitcnt lgkmcnt(3)
	v_mfma_f32_32x32x16_bf16 v[80:95], v[230:233], v[128:131], v[80:95]
	v_add_u32_e32 v211, v209, v194
	ds_read_b128 v[230:233], v211 offset:8192
	v_cvt_pk_bf16_f32 v155, v70, v71
	v_cvt_pk_bf16_f32 v156, v72, v73
	v_cvt_pk_bf16_f32 v157, v74, v75
	s_waitcnt lgkmcnt(3)
	v_mfma_f32_32x32x16_bf16 v[80:95], v[234:237], v[132:135], v[80:95]
	v_add_u32_e32 v211, v209, v195
	ds_read_b128 v[234:237], v211 offset:8192
	v_cvt_pk_bf16_f32 v158, v76, v77
	v_cvt_pk_bf16_f32 v159, v78, v79
	v_permlane32_swap_b32_e32 v212, v213
	s_waitcnt lgkmcnt(3)
	v_mfma_f32_32x32x16_bf16 v[80:95], v[238:241], v[136:139], v[80:95]
	v_add_u32_e32 v211, v209, v196
	ds_read_b128 v[238:241], v211 offset:8192
	v_add_f32_e32 v252, v212, v213
	v_fma_f32 v183, v207, v183, v252
	v_permlane32_swap_b32_e32 v152, v154
	s_waitcnt lgkmcnt(3)
	v_mfma_f32_32x32x16_bf16 v[80:95], v[242:245], v[140:143], v[80:95]
	v_add_u32_e32 v211, v209, v197
	ds_read_b128 v[242:245], v211 offset:8192
	v_permlane32_swap_b32_e32 v153, v155
	v_permlane32_swap_b32_e32 v156, v158
	v_permlane32_swap_b32_e32 v157, v159
	s_waitcnt lgkmcnt(3)
	v_mfma_f32_32x32x16_bf16 v[64:79], v[230:233], v[124:127], 0
	v_add_u32_e32 v211, v209, v198
	ds_read_b128 v[230:233], v211 offset:8192
	s_waitcnt lgkmcnt(3)
	v_mfma_f32_32x32x16_bf16 v[64:79], v[234:237], v[120:123], v[64:79]
	v_add_u32_e32 v211, v209, v199
	ds_read_b128 v[234:237], v211 offset:8192
	s_waitcnt lgkmcnt(3)
	v_mfma_f32_32x32x16_bf16 v[64:79], v[238:241], v[116:119], v[64:79]
	v_add_u32_e32 v211, v209, v200
	ds_read_b128 v[238:241], v211 offset:8192
	s_waitcnt lgkmcnt(3)
	v_mfma_f32_32x32x16_bf16 v[64:79], v[242:245], v[112:115], v[64:79]
	v_add_u32_e32 v211, v209, v201
	ds_read_b128 v[242:245], v211 offset:8192
	s_waitcnt lgkmcnt(3)
	v_mfma_f32_32x32x16_bf16 v[64:79], v[230:233], v[108:111], v[64:79]
	v_add_u32_e32 v211, 0x6000, v203
	ds_read_b128 v[230:233], v211 offset:53248
	s_waitcnt lgkmcnt(3)
	v_mfma_f32_32x32x16_bf16 v[64:79], v[234:237], v[104:107], v[64:79]
	v_add_u32_e32 v211, 0x6000, v204
	ds_read_b128 v[234:237], v211 offset:53248
	s_waitcnt lgkmcnt(3)
	v_mfma_f32_32x32x16_bf16 v[64:79], v[238:241], v[100:103], v[64:79]
	v_add_u32_e32 v211, 0x6000, v205
	ds_read_b128 v[238:241], v211 offset:53248
	v_max_f32_e32 v249, v80, v81
	v_max3_f32 v249, v249, v82, v83
	s_waitcnt lgkmcnt(3)
	v_mfma_f32_32x32x16_bf16 v[64:79], v[242:245], v[96:99], v[64:79]
	v_add_u32_e32 v211, 0x6000, v206
	ds_read_b128 v[242:245], v211 offset:53248
	v_max3_f32 v249, v249, v84, v85
	v_max3_f32 v249, v249, v86, v87
	s_waitcnt lgkmcnt(3)
	v_mfma_f32_32x32x16_bf16 v[64:79], v[230:233], v[128:131], v[64:79]
	ds_read_b64_tr_b16 v[214:215], v185
	ds_read_b64_tr_b16 v[216:217], v185 offset:2048
	v_max3_f32 v249, v249, v88, v89
	v_max3_f32 v249, v249, v90, v91
	s_waitcnt lgkmcnt(4)
	v_mfma_f32_32x32x16_bf16 v[64:79], v[234:237], v[132:135], v[64:79]
	ds_read_b64_tr_b16 v[218:219], v185 offset:4096
	ds_read_b64_tr_b16 v[220:221], v185 offset:6144
	v_max3_f32 v249, v249, v92, v93
	v_max3_f32 v249, v249, v94, v95
	s_waitcnt lgkmcnt(5)
	v_mfma_f32_32x32x16_bf16 v[64:79], v[238:241], v[136:139], v[64:79]
	ds_read_b64_tr_b16 v[222:223], v185 offset:8192
	ds_read_b64_tr_b16 v[224:225], v185 offset:10240
	s_waitcnt lgkmcnt(6)
	v_mfma_f32_32x32x16_bf16 v[64:79], v[242:245], v[140:143], v[64:79]
	ds_read_b64_tr_b16 v[226:227], v185 offset:12288
	ds_read_b64_tr_b16 v[228:229], v185 offset:14336
	s_waitcnt lgkmcnt(6)
	v_mfma_f32_32x32x16_bf16 v[0:15], v[144:147], v[214:217], v[0:15]
	ds_read_b64_tr_b16 v[214:215], v185 offset:512
	ds_read_b64_tr_b16 v[216:217], v185 offset:2560
	s_waitcnt lgkmcnt(6)
	v_mfma_f32_32x32x16_bf16 v[0:15], v[148:151], v[218:221], v[0:15]
	ds_read_b64_tr_b16 v[218:219], v185 offset:4608
	ds_read_b64_tr_b16 v[220:221], v185 offset:6656
	s_waitcnt lgkmcnt(6)
	v_mfma_f32_32x32x16_bf16 v[0:15], v[152:155], v[222:225], v[0:15]
	ds_read_b64_tr_b16 v[222:223], v185 offset:8704
	ds_read_b64_tr_b16 v[224:225], v185 offset:10752
	s_waitcnt lgkmcnt(6)
	v_mfma_f32_32x32x16_bf16 v[0:15], v[156:159], v[226:229], v[0:15]
	ds_read_b64_tr_b16 v[226:227], v185 offset:12800
	ds_read_b64_tr_b16 v[228:229], v185 offset:14848
	s_waitcnt lgkmcnt(6)
	v_mfma_f32_32x32x16_bf16 v[48:63], v[144:147], v[214:217], v[48:63]
	ds_read_b64_tr_b16 v[214:215], v185 offset:1024
	ds_read_b64_tr_b16 v[216:217], v185 offset:3072
	v_max3_f32 v249, v249, v64, v65
	v_max3_f32 v249, v249, v66, v67
	v_max3_f32 v249, v249, v68, v69
	v_max3_f32 v249, v249, v70, v71
	v_max3_f32 v249, v249, v72, v73
	v_max3_f32 v249, v249, v74, v75
	v_max3_f32 v249, v249, v76, v77
	v_max3_f32 v249, v249, v78, v79
	s_waitcnt lgkmcnt(6)
	v_mfma_f32_32x32x16_bf16 v[48:63], v[148:151], v[218:221], v[48:63]
	ds_read_b64_tr_b16 v[218:219], v185 offset:5120
	ds_read_b64_tr_b16 v[220:221], v185 offset:7168
	v_mov_b32_e32 v250, v249
	s_nop 1
	v_permlane32_swap_b32_e32 v249, v250
	v_max_f32_e32 v249, v249, v250
	v_sub_f32_e32 v250, v249, v208
	v_cmp_ge_f32_e32 vcc, s40, v250
	v_max_f32_e32 v249, v208, v249
	v_sub_f32_e32 v250, v208, v249
	s_waitcnt lgkmcnt(6)
	v_mfma_f32_32x32x16_bf16 v[48:63], v[152:155], v[222:225], v[48:63]
	ds_read_b64_tr_b16 v[222:223], v185 offset:9216
	ds_read_b64_tr_b16 v[224:225], v185 offset:11264
	v_mul_f32_e32 v250, 0x3dd53b94, v250
	v_exp_f32_e32 v250, v250
	s_cmp_eq_u64 vcc, exec
	s_cselect_b64 s[10:11], -1, 0
	v_cndmask_b32_e64 v207, v250, 1.0, s[10:11]
	v_cndmask_b32_e64 v208, v249, v208, s[10:11]
	v_mul_f32_e32 v251, 0xbdd53b94, v208
	v_fmamk_f32 v80, v80, 0x3dd53b94, v251
	s_waitcnt lgkmcnt(6)
	v_mfma_f32_32x32x16_bf16 v[48:63], v[156:159], v[226:229], v[48:63]
	ds_read_b64_tr_b16 v[226:227], v185 offset:13312
	ds_read_b64_tr_b16 v[228:229], v185 offset:15360
	v_fmamk_f32 v81, v81, 0x3dd53b94, v251
	v_fmamk_f32 v82, v82, 0x3dd53b94, v251
	v_fmamk_f32 v83, v83, 0x3dd53b94, v251
	v_fmamk_f32 v84, v84, 0x3dd53b94, v251
	v_fmamk_f32 v85, v85, 0x3dd53b94, v251
	v_fmamk_f32 v86, v86, 0x3dd53b94, v251
	v_fmamk_f32 v87, v87, 0x3dd53b94, v251
	s_waitcnt lgkmcnt(6)
	v_mfma_f32_32x32x16_bf16 v[32:47], v[144:147], v[214:217], v[32:47]
	ds_read_b64_tr_b16 v[214:215], v185 offset:1536
	ds_read_b64_tr_b16 v[216:217], v185 offset:3584
	v_fmamk_f32 v88, v88, 0x3dd53b94, v251
	v_fmamk_f32 v89, v89, 0x3dd53b94, v251
	v_fmamk_f32 v90, v90, 0x3dd53b94, v251
	v_fmamk_f32 v91, v91, 0x3dd53b94, v251
	v_fmamk_f32 v92, v92, 0x3dd53b94, v251
	v_fmamk_f32 v93, v93, 0x3dd53b94, v251
	v_fmamk_f32 v94, v94, 0x3dd53b94, v251
	s_waitcnt lgkmcnt(6)
	v_mfma_f32_32x32x16_bf16 v[32:47], v[148:151], v[218:221], v[32:47]
	ds_read_b64_tr_b16 v[218:219], v185 offset:5632
	ds_read_b64_tr_b16 v[220:221], v185 offset:7680
	v_fmamk_f32 v95, v95, 0x3dd53b94, v251
	v_exp_f32_e32 v80, v80
	v_fmamk_f32 v64, v64, 0x3dd53b94, v251
	v_exp_f32_e32 v81, v81
	v_fmamk_f32 v65, v65, 0x3dd53b94, v251
	v_add_f32_e32 v212, 0, v80
	v_exp_f32_e32 v82, v82
	s_waitcnt lgkmcnt(6)
	v_mfma_f32_32x32x16_bf16 v[32:47], v[152:155], v[222:225], v[32:47]
	ds_read_b64_tr_b16 v[222:223], v185 offset:9728
	ds_read_b64_tr_b16 v[224:225], v185 offset:11776
	v_fmamk_f32 v66, v66, 0x3dd53b94, v251
	v_add_f32_e32 v212, v81, v212
	v_exp_f32_e32 v83, v83
	v_fmamk_f32 v67, v67, 0x3dd53b94, v251
	v_add_f32_e32 v212, v82, v212
	v_exp_f32_e32 v84, v84
	v_fmamk_f32 v68, v68, 0x3dd53b94, v251
	s_waitcnt lgkmcnt(6)
	v_mfma_f32_32x32x16_bf16 v[32:47], v[156:159], v[226:229], v[32:47]
	ds_read_b64_tr_b16 v[226:227], v185 offset:13824
	ds_read_b64_tr_b16 v[228:229], v185 offset:15872
	v_add_f32_e32 v212, v83, v212
	v_exp_f32_e32 v85, v85
	v_fmamk_f32 v69, v69, 0x3dd53b94, v251
	v_add_f32_e32 v212, v84, v212
	v_exp_f32_e32 v86, v86
	v_fmamk_f32 v70, v70, 0x3dd53b94, v251
	v_add_f32_e32 v212, v85, v212
	s_waitcnt lgkmcnt(6)
	v_mfma_f32_32x32x16_bf16 v[16:31], v[144:147], v[214:217], v[16:31]
	v_exp_f32_e32 v87, v87
	v_fmamk_f32 v71, v71, 0x3dd53b94, v251
	v_add_f32_e32 v212, v86, v212
	v_exp_f32_e32 v88, v88
	v_fmamk_f32 v72, v72, 0x3dd53b94, v251
	v_add_f32_e32 v212, v87, v212
	v_exp_f32_e32 v89, v89
	s_waitcnt lgkmcnt(4)
	v_mfma_f32_32x32x16_bf16 v[16:31], v[148:151], v[218:221], v[16:31]
	v_fmamk_f32 v73, v73, 0x3dd53b94, v251
	v_add_f32_e32 v212, v88, v212
	v_exp_f32_e32 v90, v90
	v_fmamk_f32 v74, v74, 0x3dd53b94, v251
	v_add_f32_e32 v212, v89, v212
	v_exp_f32_e32 v91, v91
	v_fmamk_f32 v75, v75, 0x3dd53b94, v251
	s_waitcnt lgkmcnt(2)
	v_mfma_f32_32x32x16_bf16 v[16:31], v[152:155], v[222:225], v[16:31]
	v_add_f32_e32 v212, v90, v212
	v_exp_f32_e32 v92, v92
	v_fmamk_f32 v76, v76, 0x3dd53b94, v251
	v_add_f32_e32 v212, v91, v212
	v_exp_f32_e32 v93, v93
	v_fmamk_f32 v77, v77, 0x3dd53b94, v251
	v_add_f32_e32 v212, v92, v212
	s_waitcnt lgkmcnt(0)
	v_mfma_f32_32x32x16_bf16 v[16:31], v[156:159], v[226:229], v[16:31]
	v_exp_f32_e32 v94, v94
	v_fmamk_f32 v78, v78, 0x3dd53b94, v251
	v_add_f32_e32 v212, v93, v212
	v_exp_f32_e32 v95, v95
	v_fmamk_f32 v79, v79, 0x3dd53b94, v251
	v_add_f32_e32 v212, v94, v212
	v_add_f32_e32 v212, v95, v212
	v_cvt_pk_bf16_f32 v144, v80, v81
	v_cvt_pk_bf16_f32 v145, v82, v83
	v_cvt_pk_bf16_f32 v146, v84, v85
	v_cvt_pk_bf16_f32 v147, v86, v87
	v_cvt_pk_bf16_f32 v148, v88, v89
	v_cvt_pk_bf16_f32 v149, v90, v91
	v_cvt_pk_bf16_f32 v150, v92, v93
	v_cvt_pk_bf16_f32 v151, v94, v95
	v_permlane32_swap_b32_e32 v144, v146
	v_permlane32_swap_b32_e32 v145, v147
	v_permlane32_swap_b32_e32 v148, v150
	v_permlane32_swap_b32_e32 v149, v151
	v_cmp_gt_f32_e32 vcc, 1.0, v207
	s_cbranch_vccz .Lmla_noresc_t
	s_and_saveexec_b64 s[0:1], s[8:9]
	ds_write_b32 v182, v207 offset:128
	s_or_b64 exec, exec, s[0:1]
	s_waitcnt lgkmcnt(0)
	v_add_u32_e32 v253, s50, v181
	ds_read_b128 v[92:95], v253 offset:224
	ds_read_b128 v[88:91], v253 offset:192
	ds_read_b128 v[84:87], v253 offset:160
	ds_read_b128 v[80:83], v253 offset:128
	s_waitcnt lgkmcnt(3)
	v_pk_mul_f32 v[12:13], v[12:13], v[92:93]
	v_pk_mul_f32 v[14:15], v[14:15], v[94:95]
	v_pk_mul_f32 v[60:61], v[60:61], v[92:93]
	v_pk_mul_f32 v[62:63], v[62:63], v[94:95]
	v_pk_mul_f32 v[44:45], v[44:45], v[92:93]
	v_pk_mul_f32 v[46:47], v[46:47], v[94:95]
	v_pk_mul_f32 v[28:29], v[28:29], v[92:93]
	v_pk_mul_f32 v[30:31], v[30:31], v[94:95]
	s_waitcnt lgkmcnt(2)
	v_pk_mul_f32 v[8:9], v[8:9], v[88:89]
	v_pk_mul_f32 v[10:11], v[10:11], v[90:91]
	v_pk_mul_f32 v[56:57], v[56:57], v[88:89]
	v_pk_mul_f32 v[58:59], v[58:59], v[90:91]
	v_pk_mul_f32 v[40:41], v[40:41], v[88:89]
	v_pk_mul_f32 v[42:43], v[42:43], v[90:91]
	v_pk_mul_f32 v[24:25], v[24:25], v[88:89]
	v_pk_mul_f32 v[26:27], v[26:27], v[90:91]
	s_waitcnt lgkmcnt(1)
	v_pk_mul_f32 v[4:5], v[4:5], v[84:85]
	v_pk_mul_f32 v[6:7], v[6:7], v[86:87]
	v_pk_mul_f32 v[52:53], v[52:53], v[84:85]
	v_pk_mul_f32 v[54:55], v[54:55], v[86:87]
	v_pk_mul_f32 v[36:37], v[36:37], v[84:85]
	v_pk_mul_f32 v[38:39], v[38:39], v[86:87]
	v_pk_mul_f32 v[20:21], v[20:21], v[84:85]
	v_pk_mul_f32 v[22:23], v[22:23], v[86:87]
	s_waitcnt lgkmcnt(0)
	v_pk_mul_f32 v[0:1], v[0:1], v[80:81]
	v_pk_mul_f32 v[2:3], v[2:3], v[82:83]
	v_pk_mul_f32 v[48:49], v[48:49], v[80:81]
	v_pk_mul_f32 v[50:51], v[50:51], v[82:83]
	v_pk_mul_f32 v[32:33], v[32:33], v[80:81]
	v_pk_mul_f32 v[34:35], v[34:35], v[82:83]
	v_pk_mul_f32 v[16:17], v[16:17], v[80:81]
	v_pk_mul_f32 v[18:19], v[18:19], v[82:83]
